# hm3 loop: one M0 wait-state s_nop replaced by hoisting the m0 write above the address add (strategy 7, SALU fills the slot)
# baseline (speedup 1.0000x reference)
.LBB0_998:
	s_cmp_lt_u32 s65, 30
	s_cselect_b64 s[16:17], -1, 0
	s_and_b64 s[22:23], s[16:17], exec
	s_cselect_b32 s22, 2, 0xffffffe2
	s_cselect_b32 s37, s15, s39
	s_cselect_b32 s36, s14, s38
	s_add_i32 s22, s22, s65
	s_ashr_i32 s23, s22, 31
	s_lshl_b64 s[22:23], s[22:23], 15
	s_add_u32 s36, s36, s22
	s_addc_u32 s37, s37, s23
	s_and_b64 s[16:17], s[16:17], exec
	v_add_u32_e32 v0, s58, v224
	s_cselect_b32 s17, s25, s41
	s_cselect_b32 s16, s24, s40
	s_add_i32 s66, s58, 0
	ds_read_b128 v[146:149], v0
	ds_read_b128 v[150:153], v0 offset:1024
	ds_read_b128 v[154:157], v0 offset:2048
	ds_read_b128 v[158:161], v0 offset:3072
	v_add_u32_e32 v0, s66, v223
	ds_read_b128 v[130:133], v0 offset:16384
	ds_read_b128 v[134:137], v0 offset:17408
	ds_read_b128 v[138:141], v0 offset:18432
	ds_read_b128 v[142:145], v0 offset:19456
	s_add_i32 s66, s51, s66
	s_add_u32 s16, s16, s22
	s_addc_u32 s17, s17, s23
	s_add_i32 s22, s45, s57
	v_add_u32_e32 v0, s66, v222
	s_mov_b32 m0, s22
	ds_read_b128 v[186:189], v0 offset:32768
	ds_read_b128 v[190:193], v0 offset:33792
	ds_read_b128 v[178:181], v0 offset:34816
	ds_read_b128 v[182:185], v0 offset:35840
	ds_read_b128 v[170:173], v0 offset:36864
	ds_read_b128 v[174:177], v0 offset:37888
	ds_read_b128 v[162:165], v0 offset:38912
	ds_read_b128 v[166:169], v0 offset:39936
	global_load_lds_dwordx4 v194, s[16:17]
	s_add_i32 m0, s22, 0x2000
	s_nop 0
	global_load_lds_dwordx4 v196, s[16:17]
	s_add_i32 m0, s22, 0x4000
	s_add_u32 s16, s16, 0x4000
	s_addc_u32 s17, s17, 0
	global_load_lds_dwordx4 v194, s[16:17]
	s_add_i32 m0, s22, 0x6000
	s_nop 0
	global_load_lds_dwordx4 v196, s[16:17]
	s_add_i32 m0, s22, 0x8000
	s_nop 0
	global_load_lds_dwordx4 v194, s[36:37]
	s_add_i32 m0, s22, 0xa000
	s_and_b32 s22, s65, 7
	global_load_lds_dwordx4 v196, s[36:37]
	s_cmp_lg_u32 s22, 6
	s_cbranch_scc1 .LBB0_1035
	s_and_b32 s16, s65, 24
	s_add_i32 s16, s27, s16
	s_ashr_i32 s17, s16, 31
	s_lshl_b64 s[16:17], s[16:17], 16
	s_add_u32 s16, s31, s16
	s_addc_u32 s17, s64, s17
	s_add_u32 s16, s16, s53
	s_addc_u32 s17, s17, s54
	v_lshl_add_u64 v[208:209], s[16:17], 0, v[198:199]
	v_add_co_u32_e32 v210, vcc, s11, v208
	s_nop 1
	v_addc_co_u32_e32 v211, vcc, 0, v209, vcc
	v_add_co_u32_e32 v200, vcc, 0x3000, v208
	s_nop 1
	v_addc_co_u32_e32 v201, vcc, 0, v209, vcc
	v_add_co_u32_e32 v204, vcc, s29, v208
	s_nop 1
	v_addc_co_u32_e32 v205, vcc, 0, v209, vcc
	v_add_co_u32_e32 v212, vcc, 0x5000, v208
	s_nop 1
	v_addc_co_u32_e32 v213, vcc, 0, v209, vcc
	global_load_dwordx2 v[206:207], v[208:209], off nt
	global_load_dwordx2 v[202:203], v[200:201], off nt
	s_nop 0
	global_load_dwordx2 v[200:201], v[204:205], off nt
	s_nop 0
	global_load_dwordx2 v[204:205], v[212:213], off nt
	v_add_co_u32_e32 v212, vcc, 0x6000, v208
	s_nop 1
	v_addc_co_u32_e32 v213, vcc, 0, v209, vcc
	v_add_co_u32_e32 v208, vcc, 0x7000, v208
	s_nop 1
	v_addc_co_u32_e32 v209, vcc, 0, v209, vcc
	global_load_dwordx2 v[218:219], v[210:211], off offset:-4096 nt
	global_load_dwordx2 v[216:217], v[210:211], off nt
	s_nop 0
	global_load_dwordx2 v[212:213], v[212:213], off nt
	s_nop 0
	global_load_dwordx2 v[214:215], v[208:209], off nt
	s_cmp_lt_u32 s22, 6
	s_mov_b64 s[16:17], -1
	s_cbranch_scc1 .LBB0_1036
